# k2=2 DMA rebalance + stick-breaking attention PV step: all 8 V-fragment LDS reads issued up front into spare VGPRs, counted lgkmcnt waits, uniform act0/act1 branches once
# speedup vs baseline: 1.0236x; 1.0236x over previous
.LBB0_888:
	v_add_u32_e32 v73, s81, v159
	v_add_u32_e32 v73, v73, v164
	v_add_u32_e32 v74, 0x4800, v73
	v_add_u32_e32 v209, 0x5000, v73
	v_add_u32_e32 v235, 0x5800, v73
	v_add_u32_e32 v73, 0x6000, v73
	s_waitcnt lgkmcnt(0)
	ds_read2_b64 v[94:97], v74 offset1:4
	ds_read2_b64 v[210:213], v209 offset0:32 offset1:36
	ds_read2_b64 v[214:217], v235 offset0:64 offset1:68
	ds_read2_b64 v[218:221], v73 offset0:96 offset1:100
	ds_read2_b64 v[222:225], v74 offset0:8 offset1:12
	ds_read2_b64 v[226:229], v209 offset0:40 offset1:44
	ds_read2_b64 v[230:233], v235 offset0:72 offset1:76
	ds_read2_b64 v[236:239], v73 offset0:104 offset1:108
	v_cndmask_b32_e64 v75, 0, 1, s[94:95]
	v_cmp_ne_u32_e64 s[12:13], 1, v75
	s_andn2_b64 vcc, exec, s[94:95]
	s_cbranch_vccnz .Lsb_pv_no0
	s_waitcnt lgkmcnt(7)
	v_mfma_f32_16x16x32_bf16 v[68:71], v[94:97], v[82:85], v[68:71]
	s_waitcnt lgkmcnt(6)
	v_mfma_f32_16x16x32_bf16 v[64:67], v[210:213], v[82:85], v[64:67]
	s_waitcnt lgkmcnt(5)
	v_mfma_f32_16x16x32_bf16 v[60:63], v[214:217], v[82:85], v[60:63]
	s_waitcnt lgkmcnt(4)
	v_mfma_f32_16x16x32_bf16 v[56:59], v[218:221], v[82:85], v[56:59]
	s_waitcnt lgkmcnt(3)
	v_mfma_f32_16x16x32_bf16 v[68:71], v[222:225], v[90:93], v[68:71]
	s_waitcnt lgkmcnt(2)
	v_mfma_f32_16x16x32_bf16 v[64:67], v[226:229], v[90:93], v[64:67]
	s_waitcnt lgkmcnt(1)
	v_mfma_f32_16x16x32_bf16 v[60:63], v[230:233], v[90:93], v[60:63]
	s_waitcnt lgkmcnt(0)
	v_mfma_f32_16x16x32_bf16 v[56:59], v[236:239], v[90:93], v[56:59]
.Lsb_pv_no0:
	s_and_b64 vcc, exec, s[10:11]
	s_cbranch_vccnz .LBB0_922
	s_waitcnt lgkmcnt(7)
	v_mfma_f32_16x16x32_bf16 v[52:55], v[94:97], v[78:81], v[52:55]
	s_waitcnt lgkmcnt(6)
	v_mfma_f32_16x16x32_bf16 v[48:51], v[210:213], v[78:81], v[48:51]
	s_waitcnt lgkmcnt(5)
	v_mfma_f32_16x16x32_bf16 v[44:47], v[214:217], v[78:81], v[44:47]
	s_waitcnt lgkmcnt(4)
	v_mfma_f32_16x16x32_bf16 v[32:35], v[218:221], v[78:81], v[32:35]
	s_waitcnt lgkmcnt(3)
	v_mfma_f32_16x16x32_bf16 v[52:55], v[222:225], v[86:89], v[52:55]
	s_waitcnt lgkmcnt(2)
	v_mfma_f32_16x16x32_bf16 v[48:51], v[226:229], v[86:89], v[48:51]
	s_waitcnt lgkmcnt(1)
	v_mfma_f32_16x16x32_bf16 v[44:47], v[230:233], v[86:89], v[44:47]
	s_waitcnt lgkmcnt(0)
	v_mfma_f32_16x16x32_bf16 v[32:35], v[236:239], v[86:89], v[32:35]
	s_branch .LBB0_922

.LBB0_905:
	v_cmp_gt_f32_e32 vcc, s43, v76
	s_cmp_lg_u64 vcc, exec
	s_cselect_b64 s[0:1], -1, 0
	v_cndmask_b32_e64 v73, 0, 1, s[0:1]
	v_cmp_ne_u32_e64 s[10:11], 1, v73
	s_andn2_b64 vcc, exec, s[0:1]
	s_cbranch_vccz .LBB0_887
	s_branch .LBB0_888
.LBB0_922:
	v_cmp_gt_f32_e32 vcc, s43, v72
	v_cmp_gt_f32_e64 s[0:1], s43, v76
	s_and_b64 s[0:1], vcc, s[0:1]
	s_nop 0
	v_cndmask_b32_e64 v73, 0, 1, s[0:1]
	v_cmp_ne_u32_e32 vcc, 0, v73
	s_cmp_eq_u64 vcc, exec
	s_cselect_b64 s[0:1], -1, 0
	v_cndmask_b32_e64 v73, 0, 1, s[0:1]

	.amdhsa_kernel _Z14fwd_megakernel4Ptrs
		.amdhsa_group_segment_fixed_size 0
		.amdhsa_private_segment_fixed_size 0
		.amdhsa_kernarg_size 392
		.amdhsa_user_sgpr_count 2
		.amdhsa_user_sgpr_dispatch_ptr 0
		.amdhsa_user_sgpr_queue_ptr 0
		.amdhsa_user_sgpr_kernarg_segment_ptr 1
		.amdhsa_user_sgpr_dispatch_id 0
		.amdhsa_user_sgpr_kernarg_preload_length 0
		.amdhsa_user_sgpr_kernarg_preload_offset 0
		.amdhsa_user_sgpr_private_segment_size 0
		.amdhsa_uses_dynamic_stack 0
		.amdhsa_enable_private_segment 0
		.amdhsa_system_sgpr_workgroup_id_x 1
		.amdhsa_system_sgpr_workgroup_id_y 0
		.amdhsa_system_sgpr_workgroup_id_z 0
		.amdhsa_system_sgpr_workgroup_info 0
		.amdhsa_system_vgpr_workitem_id 2
		.amdhsa_next_free_vgpr 240
		.amdhsa_next_free_sgpr 98
		.amdhsa_accum_offset 240
		.amdhsa_reserve_vcc 1
		.amdhsa_float_round_mode_32 0
		.amdhsa_float_round_mode_16_64 0
		.amdhsa_float_denorm_mode_32 3
		.amdhsa_float_denorm_mode_16_64 3
		.amdhsa_dx10_clamp 1
		.amdhsa_ieee_mode 1
		.amdhsa_fp16_overflow 0
		.amdhsa_tg_split 0
		.amdhsa_exception_fp_ieee_invalid_op 0
		.amdhsa_exception_fp_denorm_src 0
		.amdhsa_exception_fp_ieee_div_zero 0
		.amdhsa_exception_fp_ieee_overflow 0
		.amdhsa_exception_fp_ieee_underflow 0
		.amdhsa_exception_fp_ieee_inexact 0
		.amdhsa_exception_int_div_zero 0
	.end_amdhsa_kernel

.Lfunc_end0:
	.size	_Z14fwd_megakernel4Ptrs, .Lfunc_end0-_Z14fwd_megakernel4Ptrs
	.set _Z14fwd_megakernel4Ptrs.num_vgpr, 240
	.set _Z14fwd_megakernel4Ptrs.num_agpr, 0
	.set _Z14fwd_megakernel4Ptrs.numbered_sgpr, 98
	.set _Z14fwd_megakernel4Ptrs.num_named_barrier, 0
	.set _Z14fwd_megakernel4Ptrs.private_seg_size, 0
	.set _Z14fwd_megakernel4Ptrs.uses_vcc, 1
	.set _Z14fwd_megakernel4Ptrs.uses_flat_scratch, 0
	.set _Z14fwd_megakernel4Ptrs.has_dyn_sized_stack, 0
	.set _Z14fwd_megakernel4Ptrs.has_recursion, 0
	.set _Z14fwd_megakernel4Ptrs.has_indirect_call, 0

amdhsa.kernels:
  - .agpr_count:     0
    .args:
      - .offset:         0
        .size:           136
        .value_kind:     by_value
      - .offset:         136
        .size:           4
        .value_kind:     hidden_block_count_x
      - .offset:         140
        .size:           4
        .value_kind:     hidden_block_count_y
      - .offset:         144
        .size:           4
        .value_kind:     hidden_block_count_z
      - .offset:         148
        .size:           2
        .value_kind:     hidden_group_size_x
      - .offset:         150
        .size:           2
        .value_kind:     hidden_group_size_y
      - .offset:         152
        .size:           2
        .value_kind:     hidden_group_size_z
      - .offset:         154
        .size:           2
        .value_kind:     hidden_remainder_x
      - .offset:         156
        .size:           2
        .value_kind:     hidden_remainder_y
      - .offset:         158
        .size:           2
        .value_kind:     hidden_remainder_z
      - .offset:         176
        .size:           8
        .value_kind:     hidden_global_offset_x
      - .offset:         184
        .size:           8
        .value_kind:     hidden_global_offset_y
      - .offset:         192
        .size:           8
        .value_kind:     hidden_global_offset_z
      - .offset:         200
        .size:           2
        .value_kind:     hidden_grid_dims
      - .offset:         224
        .size:           8
        .value_kind:     hidden_multigrid_sync_arg
      - .offset:         256
        .size:           4
        .value_kind:     hidden_dynamic_lds_size
    .group_segment_fixed_size: 0
    .kernarg_segment_align: 8
    .kernarg_segment_size: 392
    .language:       OpenCL C
    .language_version:
      - 2
      - 0
    .max_flat_workgroup_size: 512
    .name:           _Z14fwd_megakernel4Ptrs
    .private_segment_fixed_size: 0
    .sgpr_count:     104
    .sgpr_spill_count: 58
    .symbol:         _Z14fwd_megakernel4Ptrs.kd
    .uniform_work_group_size: 1
    .uses_dynamic_stack: false
    .vgpr_count:     240
    .vgpr_spill_count: 0
    .wavefront_size: 64
